# P0: bf16 packs in rmsnorm rows loop and weight transposes via v_cvt_pk_bf16_f32 (same RNE rounding)
# baseline (speedup 1.0000x reference)
.LBB0_11:
	s_lshl_b32 s2, s8, 1
	s_and_b32 s2, s2, 0x7fc0
	s_add_i32 s2, s2, 0xf000
	s_and_b32 s5, s2, 0xffc0
	s_lshl_b32 s2, s8, 5
	s_and_b32 s4, s2, 0x3e0
	s_lshl_b32 s2, s4, 2
	v_or_b32_e32 v13, s5, v3
	v_lshl_add_u64 v[80:81], v[10:11], 0, s[2:3]
	v_lshlrev_b32_e32 v52, 12, v13
	v_mov_b32_e32 v53, v5
	v_or_b32_e32 v13, s5, v28
	v_lshl_add_u64 v[60:61], v[80:81], 0, v[52:53]
	v_lshlrev_b32_e32 v52, 12, v13
	v_or_b32_e32 v13, s5, v29
	v_lshl_add_u64 v[62:63], v[80:81], 0, v[52:53]
	global_load_dwordx4 v[52:55], v[60:61], off
	global_load_dwordx4 v[56:59], v[62:63], off
	v_lshlrev_b32_e32 v60, 12, v13
	v_mov_b32_e32 v61, v5
	v_or_b32_e32 v13, s5, v30
	v_lshl_add_u64 v[68:69], v[80:81], 0, v[60:61]
	v_lshlrev_b32_e32 v60, 12, v13
	v_or_b32_e32 v13, s5, v31
	v_lshl_add_u64 v[70:71], v[80:81], 0, v[60:61]
	global_load_dwordx4 v[60:63], v[68:69], off
	global_load_dwordx4 v[64:67], v[70:71], off
	v_lshlrev_b32_e32 v68, 12, v13
	v_mov_b32_e32 v69, v5
	v_or_b32_e32 v13, s5, v32
	v_lshl_add_u64 v[76:77], v[80:81], 0, v[68:69]
	v_lshlrev_b32_e32 v68, 12, v13
	v_lshl_add_u64 v[78:79], v[80:81], 0, v[68:69]
	global_load_dwordx4 v[68:71], v[76:77], off
	global_load_dwordx4 v[72:75], v[78:79], off
	v_or_b32_e32 v13, s5, v33
	v_lshlrev_b32_e32 v76, 12, v13
	v_mov_b32_e32 v77, v5
	v_lshl_add_u64 v[76:77], v[80:81], 0, v[76:77]
	v_or_b32_e32 v13, s5, v34
	global_load_dwordx4 v[76:79], v[76:77], off
	v_lshlrev_b32_e32 v82, 12, v13
	v_mov_b32_e32 v83, v5
	v_lshl_add_u64 v[80:81], v[80:81], 0, v[82:83]
	global_load_dwordx4 v[80:83], v[80:81], off
	s_lshl_b32 s2, s5, 1
	v_lshl_add_u64 v[84:85], v[6:7], 0, s[2:3]
	s_waitcnt vmcnt(7)
	ds_write2_b32 v36, v52, v53 offset1:1
	ds_write2_b32 v36, v54, v55 offset0:2 offset1:3
	s_waitcnt vmcnt(6)
	ds_write2_b32 v37, v56, v57 offset1:1
	ds_write2_b32 v38, v58, v59 offset1:1
	s_waitcnt vmcnt(5)
	ds_write2_b32 v39, v60, v61 offset1:1
	ds_write2_b32 v40, v62, v63 offset1:1
	s_waitcnt vmcnt(4)
	ds_write2_b32 v41, v64, v65 offset1:1
	ds_write2_b32 v42, v66, v67 offset1:1
	s_waitcnt vmcnt(3)
	ds_write2_b32 v43, v68, v69 offset1:1
	ds_write2_b32 v44, v70, v71 offset1:1
	s_waitcnt vmcnt(2)
	ds_write2_b32 v45, v72, v73 offset1:1
	ds_write2_b32 v46, v74, v75 offset1:1
	s_waitcnt vmcnt(1)
	ds_write2_b32 v47, v76, v77 offset1:1
	ds_write2_b32 v48, v78, v79 offset1:1
	s_waitcnt vmcnt(0)
	ds_write2_b32 v49, v80, v81 offset1:1
	ds_write2_b32 v50, v82, v83 offset1:1
	s_waitcnt lgkmcnt(0)
	ds_read2_b32 v[56:57], v35 offset0:33 offset1:41
	ds_read2_b32 v[58:59], v35 offset1:8
	ds_read2_b32 v[60:61], v35 offset0:66 offset1:74
	ds_read2_b32 v[62:63], v35 offset0:99 offset1:107
	ds_read2_b32 v[64:65], v35 offset0:132 offset1:140
	ds_read2_b32 v[66:67], v35 offset0:165 offset1:173
	ds_read2_b32 v[68:69], v35 offset0:198 offset1:206
	ds_read2_b32 v[70:71], v35 offset0:231 offset1:239
	s_waitcnt lgkmcnt(6)
	s_waitcnt lgkmcnt(5)
	s_waitcnt lgkmcnt(3)
	s_waitcnt lgkmcnt(1)
	v_cvt_pk_bf16_f32 v52, v58, v56
	v_or_b32_e32 v13, s4, v3
	s_waitcnt lgkmcnt(0)
	v_lshlrev_b32_e32 v72, 11, v13
	v_bfe_u32 v13, v59, 16, 1
	v_mov_b32_e32 v73, v5
	v_add3_u32 v13, v59, v13, s6
	v_bfe_u32 v15, v57, 16, 1
	v_cvt_pk_bf16_f32 v53, v60, v62
	v_cvt_pk_bf16_f32 v54, v64, v66
	v_cvt_pk_bf16_f32 v55, v68, v70
	v_lshl_add_u64 v[72:73], v[84:85], 0, v[72:73]
	v_lshrrev_b32_e32 v13, 16, v13
	v_add3_u32 v15, v57, v15, s6
	global_store_dwordx4 v[72:73], v[52:55], off
	v_mov_b32_e32 v57, v5
	ds_read2_b32 v[58:59], v35 offset0:16 offset1:24
	v_and_or_b32 v52, v15, s7, v13
	v_cvt_pk_bf16_f32 v53, v61, v63
	v_cvt_pk_bf16_f32 v54, v65, v67
	v_cvt_pk_bf16_f32 v55, v69, v71
	v_or_b32_e32 v13, s4, v28
	v_lshlrev_b32_e32 v56, 11, v13
	v_lshl_add_u64 v[56:57], v[84:85], 0, v[56:57]
	global_store_dwordx4 v[56:57], v[52:55], off
	ds_read2_b32 v[56:57], v35 offset0:49 offset1:57
	ds_read2_b32 v[60:61], v35 offset0:82 offset1:90
	ds_read2_b32 v[62:63], v35 offset0:115 offset1:123
	s_waitcnt lgkmcnt(3)
	s_waitcnt lgkmcnt(2)
	ds_read2_b32 v[64:65], v35 offset0:148 offset1:156
	ds_read2_b32 v[66:67], v35 offset0:181 offset1:189
	v_cvt_pk_bf16_f32 v52, v58, v56
	s_waitcnt lgkmcnt(3)
	s_waitcnt lgkmcnt(2)
	ds_read2_b32 v[68:69], v35 offset0:214 offset1:222
	ds_read2_b32 v[70:71], v35 offset0:247 offset1:255
	v_cvt_pk_bf16_f32 v53, v60, v62
	s_waitcnt lgkmcnt(3)
	s_waitcnt lgkmcnt(2)
	v_cvt_pk_bf16_f32 v54, v64, v66
	s_waitcnt lgkmcnt(1)
	s_waitcnt lgkmcnt(0)
	v_cvt_pk_bf16_f32 v55, v68, v70
	v_or_b32_e32 v13, s4, v29
	v_lshlrev_b32_e32 v72, 11, v13
	v_bfe_u32 v13, v59, 16, 1
	v_mov_b32_e32 v73, v5
	v_add3_u32 v13, v59, v13, s6
	v_bfe_u32 v15, v57, 16, 1
	v_lshl_add_u64 v[72:73], v[84:85], 0, v[72:73]
	v_lshrrev_b32_e32 v13, 16, v13
	v_add3_u32 v15, v57, v15, s6
	global_store_dwordx4 v[72:73], v[52:55], off
	v_mov_b32_e32 v57, v5
	s_nop 0
	v_and_or_b32 v52, v15, s7, v13
	v_cvt_pk_bf16_f32 v53, v61, v63
	v_cvt_pk_bf16_f32 v54, v65, v67
	v_cvt_pk_bf16_f32 v55, v69, v71
	v_or_b32_e32 v13, s4, v30
	v_lshlrev_b32_e32 v56, 11, v13
	v_lshl_add_u64 v[56:57], v[84:85], 0, v[56:57]
	global_store_dwordx4 v[56:57], v[52:55], off
	s_waitcnt lgkmcnt(0)
	s_cbranch_execnz .LBB0_8
.LBB0_12:
	s_ashr_i32 s4, s8, 8
	s_cmp_eq_u32 s4, 1
	s_cselect_b32 s2, 0x200, 0
	s_cmp_lg_u32 s4, 2
	s_cselect_b32 s2, s2, 0x400
	s_cmp_lg_u32 s4, 3
	s_cselect_b32 s2, s2, 0x608
	s_cmp_lg_u32 s4, 4
	s_cselect_b32 s2, s2, 0x808
	s_cmp_lg_u32 s4, 5
	s_load_dwordx16 s[36:51], s[0:1], 0x40
	s_cselect_b32 s2, s2, 0xa08
	s_cmp_lg_u32 s4, 6
	s_cselect_b32 s2, s2, 0xc08
	s_cmp_lg_u32 s4, 7
	s_cselect_b32 s2, s2, 0xe08
	s_lshl_b32 s9, s4, 9
	s_lshl_b32 s4, s8, 5
	s_and_b32 s10, s4, 0x1e0
	s_lshl_b64 s[4:5], s[2:3], 2
	s_waitcnt lgkmcnt(0)
	s_add_u32 s2, s36, s4
	s_addc_u32 s5, s37, s5
	s_lshl_b32 s4, s10, 2
	s_add_u32 s4, s2, s4
	s_addc_u32 s5, s5, 0
	v_lshl_add_u64 v[80:81], s[4:5], 0, v[4:5]
	v_mov_b32_e32 v13, v5
	v_lshl_add_u64 v[60:61], v[80:81], 0, v[12:13]
	v_mov_b32_e32 v15, v5
	v_lshl_add_u64 v[62:63], v[80:81], 0, v[14:15]
	global_load_dwordx4 v[52:55], v[60:61], off
	global_load_dwordx4 v[56:59], v[62:63], off
	v_mov_b32_e32 v17, v5
	v_lshl_add_u64 v[60:61], v[80:81], 0, v[16:17]
	global_load_dwordx4 v[60:63], v[60:61], off
	v_mov_b32_e32 v19, v5
	v_lshl_add_u64 v[64:65], v[80:81], 0, v[18:19]
	v_mov_b32_e32 v21, v5
	global_load_dwordx4 v[64:67], v[64:65], off
	v_lshl_add_u64 v[68:69], v[80:81], 0, v[20:21]
	v_mov_b32_e32 v23, v5
	global_load_dwordx4 v[68:71], v[68:69], off
	v_lshl_add_u64 v[72:73], v[80:81], 0, v[22:23]
	v_mov_b32_e32 v25, v5
	global_load_dwordx4 v[72:75], v[72:73], off
	v_lshl_add_u64 v[76:77], v[80:81], 0, v[24:25]
	v_mov_b32_e32 v27, v5
	global_load_dwordx4 v[76:79], v[76:77], off
	v_lshl_add_u64 v[80:81], v[80:81], 0, v[26:27]
	global_load_dwordx4 v[80:83], v[80:81], off
	s_or_b32 s2, s9, s10
	v_or_b32_e32 v84, s2, v3
	v_ashrrev_i32_e32 v85, 31, v84
	v_lshlrev_b64 v[84:85], 11, v[84:85]
	v_lshl_add_u64 v[84:85], v[8:9], 0, v[84:85]
	s_waitcnt vmcnt(7)
	ds_write2_b32 v36, v52, v53 offset1:1
	ds_write2_b32 v36, v54, v55 offset0:2 offset1:3
	s_waitcnt vmcnt(6)
	ds_write2_b32 v37, v56, v57 offset1:1
	ds_write2_b32 v38, v58, v59 offset1:1
	s_waitcnt vmcnt(5)
	ds_write2_b32 v39, v60, v61 offset1:1
	ds_write2_b32 v40, v62, v63 offset1:1
	s_waitcnt vmcnt(4)
	ds_write2_b32 v41, v64, v65 offset1:1
	ds_write2_b32 v42, v66, v67 offset1:1
	s_waitcnt vmcnt(3)
	ds_write2_b32 v43, v68, v69 offset1:1
	ds_write2_b32 v44, v70, v71 offset1:1
	s_waitcnt vmcnt(2)
	ds_write2_b32 v45, v72, v73 offset1:1
	ds_write2_b32 v46, v74, v75 offset1:1
	s_waitcnt vmcnt(1)
	ds_write2_b32 v47, v76, v77 offset1:1
	ds_write2_b32 v48, v78, v79 offset1:1
	s_waitcnt vmcnt(0)
	ds_write2_b32 v49, v80, v81 offset1:1
	ds_write2_b32 v50, v82, v83 offset1:1
	s_waitcnt lgkmcnt(0)
	ds_read2_b32 v[56:57], v35 offset0:33 offset1:41
	ds_read2_b32 v[52:53], v35 offset1:8
	ds_read2_b32 v[58:59], v35 offset0:66 offset1:74
	ds_read2_b32 v[60:61], v35 offset0:99 offset1:107
	ds_read2_b32 v[62:63], v35 offset0:132 offset1:140
	ds_read2_b32 v[64:65], v35 offset0:165 offset1:173
	ds_read2_b32 v[66:67], v35 offset0:198 offset1:206
	ds_read2_b32 v[68:69], v35 offset0:231 offset1:239
	s_waitcnt lgkmcnt(6)
	s_waitcnt lgkmcnt(5)
	s_waitcnt lgkmcnt(3)
	s_waitcnt lgkmcnt(1)
	s_waitcnt lgkmcnt(0)
	v_bfe_u32 v51, v53, 16, 1
	v_bfe_u32 v70, v57, 16, 1
	v_add3_u32 v51, v53, v51, s6
	v_lshrrev_b32_e32 v51, 16, v51
	v_cvt_pk_bf16_f32 v52, v52, v56
	v_cvt_pk_bf16_f32 v53, v58, v60
	v_cvt_pk_bf16_f32 v54, v62, v64
	v_cvt_pk_bf16_f32 v55, v66, v68
	v_add3_u32 v13, v57, v70, s6
	global_store_dwordx4 v[84:85], v[52:55], off
	s_nop 1
	v_and_or_b32 v52, v13, s7, v51
	v_cvt_pk_bf16_f32 v15, v59, v61
	v_mov_b32_e32 v53, v15
	v_cvt_pk_bf16_f32 v54, v63, v65
	v_or_b32_e32 v56, s2, v28
	v_ashrrev_i32_e32 v57, 31, v56
	v_lshlrev_b64 v[56:57], 11, v[56:57]
	v_cvt_pk_bf16_f32 v55, v67, v69
	ds_read2_b32 v[58:59], v35 offset0:16 offset1:24
	v_lshl_add_u64 v[56:57], v[8:9], 0, v[56:57]
	global_store_dwordx4 v[56:57], v[52:55], off
	ds_read2_b32 v[56:57], v35 offset0:49 offset1:57
	ds_read2_b32 v[60:61], v35 offset0:82 offset1:90
	ds_read2_b32 v[62:63], v35 offset0:115 offset1:123
	s_waitcnt lgkmcnt(3)
	s_waitcnt lgkmcnt(2)
	ds_read2_b32 v[64:65], v35 offset0:148 offset1:156
	ds_read2_b32 v[66:67], v35 offset0:181 offset1:189
	v_cvt_pk_bf16_f32 v52, v58, v56
	s_waitcnt lgkmcnt(3)
	s_waitcnt lgkmcnt(2)
	ds_read2_b32 v[68:69], v35 offset0:214 offset1:222
	ds_read2_b32 v[70:71], v35 offset0:247 offset1:255
	v_cvt_pk_bf16_f32 v53, v60, v62
	s_waitcnt lgkmcnt(3)
	s_waitcnt lgkmcnt(2)
	v_cvt_pk_bf16_f32 v54, v64, v66
	s_waitcnt lgkmcnt(1)
	s_waitcnt lgkmcnt(0)
	v_or_b32_e32 v72, s2, v29
	v_cvt_pk_bf16_f32 v55, v68, v70
	v_ashrrev_i32_e32 v73, 31, v72
	v_bfe_u32 v13, v59, 16, 1
	v_lshlrev_b64 v[72:73], 11, v[72:73]
	v_add3_u32 v13, v59, v13, s6
	v_bfe_u32 v15, v57, 16, 1
	v_lshl_add_u64 v[72:73], v[8:9], 0, v[72:73]
	v_lshrrev_b32_e32 v13, 16, v13
	v_add3_u32 v15, v57, v15, s6
	global_store_dwordx4 v[72:73], v[52:55], off
	v_or_b32_e32 v56, s2, v30
	v_ashrrev_i32_e32 v57, 31, v56
	v_and_or_b32 v52, v15, s7, v13
	v_cvt_pk_bf16_f32 v53, v61, v63
	v_cvt_pk_bf16_f32 v54, v65, v67
	v_lshlrev_b64 v[56:57], 11, v[56:57]
	v_cvt_pk_bf16_f32 v55, v69, v71
	v_lshl_add_u64 v[56:57], v[8:9], 0, v[56:57]
	global_store_dwordx4 v[56:57], v[52:55], off
	s_waitcnt lgkmcnt(0)
	s_branch .LBB0_8

.LBB0_63:
	v_pk_mul_f32 v[186:187], v[162:163], v[162:163]
	v_pk_mul_f32 v[200:201], v[164:165], v[164:165]
	v_pk_mul_f32 v[202:203], v[170:171], v[170:171]
	v_pk_mul_f32 v[204:205], v[172:173], v[172:173]
	v_mov_b32_e32 v206, v202
	v_mov_b32_e32 v207, v205
	v_pk_mov_b32 v[202:203], v[202:203], v[204:205] op_sel:[1,0]
	v_mov_b32_e32 v204, v186
	v_mov_b32_e32 v205, v201
	v_pk_mov_b32 v[186:187], v[186:187], v[200:201] op_sel:[1,0]
	v_pk_add_f32 v[202:203], v[202:203], v[206:207]
	v_pk_add_f32 v[186:187], v[186:187], v[204:205]
	v_pk_add_f32 v[202:203], v[202:203], v[202:203] op_sel_hi:[0,1]
	v_pk_add_f32 v[186:187], v[186:187], v[186:187] op_sel_hi:[0,1]
	v_mul_f32_e32 v186, v174, v174
	v_pk_fma_f32 v[200:201], v[174:175], v[174:175], v[186:187] op_sel_hi:[1,1,0]
	v_mul_f32_e32 v186, v176, v176
	v_pk_fma_f32 v[204:205], v[176:177], v[176:177], v[186:187] op_sel_hi:[1,1,0]
	v_mul_f32_e32 v200, v166, v166
	v_mul_f32_e32 v204, v167, v167
	v_mul_f32_e32 v202, v168, v168
	v_mul_f32_e32 v186, v169, v169
	v_pk_add_f32 v[200:201], v[200:201], v[204:205]
	v_pk_add_f32 v[186:187], v[202:203], v[186:187]
	s_nop 0
	v_pk_add_f32 v[186:187], v[200:201], v[186:187]
	s_nop 0
	v_add_f32_e32 v186, v186, v187
	s_waitcnt lgkmcnt(0)
	s_nop 1
	v_add_f32_dpp v186, v186, v186 quad_perm:[1,0,3,2] row_mask:0xf bank_mask:0xf
	s_waitcnt lgkmcnt(0)
	s_nop 1
	v_add_f32_dpp v186, v186, v186 quad_perm:[2,3,0,1] row_mask:0xf bank_mask:0xf
	s_waitcnt lgkmcnt(0)
	s_nop 1
	v_add_f32_dpp v187, v186, v186 row_shl:4 row_mask:0xf bank_mask:0x5
	v_add_f32_dpp v187, v186, v186 row_shr:4 row_mask:0xf bank_mask:0xa
	v_mov_b32_e32 v186, v187
	s_waitcnt lgkmcnt(0)
	s_nop 1
	v_add_f32_dpp v186, v186, v186 row_ror:8 row_mask:0xf bank_mask:0xf
	s_waitcnt lgkmcnt(0)
	v_mov_b32_e32 v187, v186
	s_nop 1
	v_permlane16_swap_b32_e32 v186, v187
	v_add_f32_e32 v186, v186, v187
	ds_bpermute_b32 v187, v193, v186
	s_waitcnt lgkmcnt(0)
	v_add_f32_e32 v186, v186, v187
	v_fmamk_f32 v186, v186, 0x3a800000, v179
	v_mul_f32_e32 v187, 0x4f800000, v186
	v_cmp_gt_f32_e32 vcc, s21, v186
	s_nop 1
	v_cndmask_b32_e32 v186, v186, v187, vcc
	v_sqrt_f32_e32 v187, v186
	s_nop 0
	v_add_u32_e32 v200, -1, v187
	v_add_u32_e32 v201, 1, v187
	v_fma_f32 v202, -v200, v187, v186
	v_fma_f32 v203, -v201, v187, v186
	v_cmp_ge_f32_e64 s[0:1], 0, v202
	s_nop 1
	v_cndmask_b32_e64 v187, v187, v200, s[0:1]
	v_cmp_lt_f32_e64 s[0:1], 0, v203
	s_nop 1
	v_cndmask_b32_e64 v187, v187, v201, s[0:1]
	v_mul_f32_e32 v200, 0x37800000, v187
	v_cndmask_b32_e32 v187, v187, v200, vcc
	v_cmp_class_f32_e32 vcc, v186, v194
	s_nop 1
	v_cndmask_b32_e32 v186, v187, v186, vcc
	v_div_scale_f32 v187, s[0:1], v186, v186, 1.0
	v_rcp_f32_e32 v200, v187
	v_div_scale_f32 v201, vcc, 1.0, v186, 1.0
	v_fma_f32 v202, -v187, v200, 1.0
	v_fmac_f32_e32 v200, v202, v200
	v_mul_f32_e32 v202, v201, v200
	v_fma_f32 v203, -v187, v202, v201
	v_fmac_f32_e32 v202, v203, v200
	v_fma_f32 v187, -v187, v202, v201
	v_div_fmas_f32 v187, v187, v200, v202
	v_div_fixup_f32 v200, v187, v186, 1.0
	v_pk_mul_f32 v[170:171], v[170:171], v[200:201] op_sel_hi:[1,0]
	v_pk_mul_f32 v[172:173], v[172:173], v[200:201] op_sel_hi:[1,0]
	v_pk_mul_f32 v[186:187], v[2:3], v[170:171]
	v_pk_mul_f32 v[172:173], v[4:5], v[172:173]
	v_cvt_pk_bf16_f32 v171, v186, v187
	v_cvt_pk_bf16_f32 v170, v172, v173
	v_mov_b32_e32 v203, v170
	v_mov_b32_e32 v202, v171
	v_lshl_add_u64 v[170:171], s[72:73], 0, v[184:185]
	v_add_co_u32_e32 v170, vcc, s45, v170
	v_mul_f32_e32 v207, v173, v69
	s_nop 0
	v_addc_co_u32_e32 v171, vcc, 0, v171, vcc
	global_store_dwordx2 v[170:171], v[202:203], off
	v_pk_mul_f32 v[202:203], v[162:163], v[200:201] op_sel_hi:[1,0]
	v_pk_mul_f32 v[162:163], v[164:165], v[200:201] op_sel_hi:[1,0]
	v_pk_mul_f32 v[164:165], v[6:7], v[202:203]
	v_pk_mul_f32 v[162:163], v[8:9], v[162:163]
	v_cvt_pk_bf16_f32 v202, v164, v165
	v_cvt_pk_bf16_f32 v201, v162, v163
	v_mov_b32_e32 v203, v201
	global_store_dwordx2 v[170:171], v[202:203], off offset:512
	v_pk_mul_f32 v[202:203], v[174:175], v[200:201] op_sel_hi:[1,0]
	v_pk_mul_f32 v[174:175], v[176:177], v[200:201] op_sel_hi:[1,0]
	v_pk_mul_f32 v[176:177], v[10:11], v[202:203]
	v_pk_mul_f32 v[174:175], v[12:13], v[174:175]
	v_cvt_pk_bf16_f32 v202, v176, v177
	v_cvt_pk_bf16_f32 v201, v174, v175
	v_mov_b32_e32 v203, v201
	v_pk_mul_f32 v[204:205], v[166:167], v[200:201] op_sel_hi:[1,0]
	v_pk_mul_f32 v[166:167], v[168:169], v[200:201] op_sel_hi:[1,0]
	v_mul_f32_e32 v200, v19, v187
	v_mul_f32_e32 v201, v21, v173
	v_fmac_f32_e32 v200, v18, v186
	v_fmac_f32_e32 v201, v20, v172
	v_pk_mul_f32 v[168:169], v[14:15], v[204:205]
	v_add_f32_e32 v200, v200, v201
	v_mul_f32_e32 v201, v23, v165
	v_mul_f32_e32 v204, v25, v163
	v_fmac_f32_e32 v201, v22, v164
	v_fmac_f32_e32 v204, v24, v162
	v_add_f32_e32 v200, 0, v200
	v_add_f32_e32 v201, v201, v204
	v_add_f32_e32 v200, v201, v200
	v_mul_f32_e32 v201, v27, v177
	v_mul_f32_e32 v204, v29, v175
	v_fmac_f32_e32 v201, v26, v176
	v_fmac_f32_e32 v204, v28, v174
	v_pk_mul_f32 v[166:167], v[16:17], v[166:167]
	v_add_f32_e32 v201, v201, v204
	v_add_f32_e32 v200, v201, v200
	v_mul_f32_e32 v201, v31, v169
	v_mul_f32_e32 v204, v33, v167
	v_fmac_f32_e32 v201, v30, v168
	v_fmac_f32_e32 v204, v32, v166
	v_add_f32_e32 v201, v201, v204
	v_mul_f32_e32 v204, v187, v35
	v_mul_f32_e32 v205, v173, v37
	v_fmac_f32_e32 v204, v186, v34
	v_fmac_f32_e32 v205, v172, v36
	v_add_f32_e32 v204, v204, v205
	v_mul_f32_e32 v205, v165, v39
	v_mul_f32_e32 v206, v163, v41
	v_fmac_f32_e32 v205, v164, v38
	v_fmac_f32_e32 v206, v162, v40
	v_add_f32_e32 v204, 0, v204
	v_add_f32_e32 v205, v205, v206
	v_add_f32_e32 v204, v204, v205
	v_mul_f32_e32 v205, v177, v43
	v_mul_f32_e32 v206, v175, v45
	v_fmac_f32_e32 v205, v176, v42
	v_fmac_f32_e32 v206, v174, v44
	v_add_f32_e32 v205, v205, v206
	v_add_f32_e32 v204, v204, v205
	v_mul_f32_e32 v205, v169, v47
	v_mul_f32_e32 v206, v167, v49
	v_fmac_f32_e32 v205, v168, v46
	v_fmac_f32_e32 v206, v166, v48
	v_add_f32_e32 v205, v205, v206
	v_add_f32_e32 v204, v204, v205
	global_store_dwordx2 v[170:171], v[202:203], off offset:1024
	s_waitcnt lgkmcnt(0)
	s_nop 1
	v_add_f32_dpp v203, v204, v204 quad_perm:[1,0,3,2] row_mask:0xf bank_mask:0xf
	v_cvt_pk_bf16_f32 v211, v166, v167
	s_waitcnt lgkmcnt(0)
	s_nop 1
	v_add_f32_dpp v203, v203, v203 quad_perm:[2,3,0,1] row_mask:0xf bank_mask:0xf
	v_cvt_pk_bf16_f32 v210, v168, v169
	v_mul_f32_e32 v205, v173, v53
	v_fmac_f32_e32 v205, v172, v52
	s_waitcnt lgkmcnt(0)
	s_nop 1
	v_add_f32_dpp v204, v203, v203 row_shl:4 row_mask:0xf bank_mask:0x5
	v_add_f32_dpp v204, v203, v203 row_shr:4 row_mask:0xf bank_mask:0xa
	v_mov_b32_e32 v203, v204
	v_mul_f32_e32 v206, v163, v57
	v_fmac_f32_e32 v206, v162, v56
	v_fmac_f32_e32 v207, v172, v68
	v_mul_f32_e32 v208, v163, v73
	s_waitcnt lgkmcnt(0)
	s_nop 1
	v_add_f32_dpp v203, v203, v203 row_ror:8 row_mask:0xf bank_mask:0xf
	v_fmac_f32_e32 v208, v162, v72
	v_mul_f32_e32 v209, v173, v85
	v_fmac_f32_e32 v209, v172, v84
	v_mul_f32_e32 v214, v163, v89
	s_waitcnt lgkmcnt(0)
	v_mov_b32_e32 v204, v203
	s_nop 1
	v_permlane16_swap_b32_e32 v203, v204
	v_add_f32_e32 v202, v203, v204
	v_mul_f32_e32 v204, v187, v51
	v_fmac_f32_e32 v204, v186, v50
	v_add_f32_e32 v204, v204, v205
	v_mul_f32_e32 v205, v165, v55
	v_fmac_f32_e32 v205, v164, v54
	v_add_f32_e32 v204, 0, v204
	v_add_f32_e32 v205, v205, v206
	v_add_f32_e32 v204, v204, v205
	v_mul_f32_e32 v205, v177, v59
	v_mul_f32_e32 v206, v175, v61
	v_fmac_f32_e32 v205, v176, v58
	v_fmac_f32_e32 v206, v174, v60
	v_add_f32_e32 v205, v205, v206
	v_add_f32_e32 v204, v204, v205
	v_mul_f32_e32 v205, v169, v63
	v_mul_f32_e32 v206, v167, v65
	v_fmac_f32_e32 v205, v168, v62
	v_fmac_f32_e32 v206, v166, v64
	v_add_f32_e32 v205, v205, v206
	v_mul_f32_e32 v206, v187, v67
	v_fmac_f32_e32 v206, v186, v66
	v_add_f32_e32 v206, v206, v207
	v_mul_f32_e32 v207, v165, v71
	v_fmac_f32_e32 v207, v164, v70
	v_add_f32_e32 v206, 0, v206
	v_add_f32_e32 v207, v207, v208
	v_add_f32_e32 v206, v206, v207
	v_mul_f32_e32 v207, v177, v75
	v_mul_f32_e32 v208, v175, v77
	v_fmac_f32_e32 v207, v176, v74
	v_fmac_f32_e32 v208, v174, v76
	v_add_f32_e32 v207, v207, v208
	v_add_f32_e32 v206, v206, v207
	v_mul_f32_e32 v207, v169, v79
	v_mul_f32_e32 v208, v167, v81
	v_fmac_f32_e32 v207, v168, v78
	v_fmac_f32_e32 v208, v166, v80
	v_add_f32_e32 v207, v207, v208
	v_mul_f32_e32 v208, v187, v83
	v_fmac_f32_e32 v208, v186, v82
	v_add_f32_e32 v208, v208, v209
	v_mul_f32_e32 v209, v165, v87
	v_fmac_f32_e32 v209, v164, v86
	v_fmac_f32_e32 v214, v162, v88
	v_add_f32_e32 v208, 0, v208
	v_add_f32_e32 v209, v209, v214
	v_add_f32_e32 v208, v208, v209
	v_mul_f32_e32 v209, v177, v91
	v_mul_f32_e32 v214, v175, v93
	v_fmac_f32_e32 v209, v176, v90
	v_fmac_f32_e32 v214, v174, v92
	v_add_f32_e32 v209, v209, v214
	v_add_f32_e32 v208, v208, v209
	v_mul_f32_e32 v209, v169, v95
	v_mul_f32_e32 v214, v167, v97
	v_fmac_f32_e32 v209, v168, v94
	v_fmac_f32_e32 v214, v166, v96
	v_add_f32_e32 v209, v209, v214
	v_mul_f32_e32 v214, v187, v99
	v_mul_f32_e32 v215, v173, v101
	v_fmac_f32_e32 v214, v186, v98
	v_fmac_f32_e32 v215, v172, v100
	v_add_f32_e32 v214, v214, v215
	v_mul_f32_e32 v215, v165, v103
	v_mul_f32_e32 v216, v163, v105
	v_fmac_f32_e32 v215, v164, v102
	v_fmac_f32_e32 v216, v162, v104
	v_add_f32_e32 v214, 0, v214
	v_add_f32_e32 v215, v215, v216
	v_add_f32_e32 v214, v214, v215
	v_mul_f32_e32 v215, v177, v107
	v_mul_f32_e32 v216, v175, v109
	v_fmac_f32_e32 v215, v176, v106
	v_fmac_f32_e32 v216, v174, v108
	v_add_f32_e32 v215, v215, v216
	v_add_f32_e32 v214, v214, v215
	v_mul_f32_e32 v215, v169, v111
	v_mul_f32_e32 v216, v167, v113
	v_fmac_f32_e32 v215, v168, v110
	v_fmac_f32_e32 v216, v166, v112
	v_add_f32_e32 v215, v215, v216
	v_mul_f32_e32 v216, v187, v115
	v_mul_f32_e32 v217, v173, v117
	v_fmac_f32_e32 v216, v186, v114
	v_fmac_f32_e32 v217, v172, v116
	v_add_f32_e32 v216, v216, v217
	v_mul_f32_e32 v217, v165, v119
	v_mul_f32_e32 v218, v163, v121
	v_fmac_f32_e32 v217, v164, v118
	v_fmac_f32_e32 v218, v162, v120
	v_mul_f32_e32 v187, v187, v131
	v_mul_f32_e32 v173, v173, v133
	v_mul_f32_e32 v165, v165, v135
	v_mul_f32_e32 v163, v163, v137
	v_add_f32_e32 v216, 0, v216
	v_add_f32_e32 v217, v217, v218
	v_fmac_f32_e32 v187, v186, v130
	v_fmac_f32_e32 v173, v172, v132
	v_fmac_f32_e32 v165, v164, v134
	v_fmac_f32_e32 v163, v162, v136
	v_add_f32_e32 v216, v216, v217
	v_mul_f32_e32 v217, v177, v123
	v_mul_f32_e32 v218, v175, v125
	v_add_f32_e32 v172, v187, v173
	v_add_f32_e32 v162, v165, v163
	v_mul_f32_e32 v163, v177, v139
	v_mul_f32_e32 v164, v175, v141
	v_fmac_f32_e32 v217, v176, v122
	v_fmac_f32_e32 v218, v174, v124
	v_add_f32_e32 v172, 0, v172
	v_fmac_f32_e32 v163, v176, v138
	v_fmac_f32_e32 v164, v174, v140
	v_add_f32_e32 v217, v217, v218
	v_add_f32_e32 v162, v172, v162
	v_add_f32_e32 v163, v163, v164
	v_add_f32_e32 v216, v216, v217
	v_mul_f32_e32 v217, v169, v127
	v_mul_f32_e32 v218, v167, v129
	v_add_f32_e32 v162, v162, v163
	v_mul_f32_e32 v163, v169, v143
	v_mul_f32_e32 v164, v167, v145
	v_fmac_f32_e32 v217, v168, v126
	v_fmac_f32_e32 v218, v166, v128
	v_fmac_f32_e32 v163, v168, v142
	v_fmac_f32_e32 v164, v166, v144
	v_add_f32_e32 v217, v217, v218
	v_add_f32_e32 v163, v163, v164
	v_add_f32_e32 v200, v201, v200
	v_add_f32_e32 v204, v204, v205
	v_add_f32_e32 v206, v206, v207
	v_add_f32_e32 v208, v208, v209
	v_add_f32_e32 v214, v214, v215
	v_add_f32_e32 v216, v216, v217
	v_add_f32_e32 v162, v162, v163
	s_waitcnt lgkmcnt(6)
	s_nop 1
	v_add_f32_dpp v200, v200, v200 quad_perm:[1,0,3,2] row_mask:0xf bank_mask:0xf
	s_waitcnt lgkmcnt(5)
	s_nop 1
	v_add_f32_dpp v204, v204, v204 quad_perm:[1,0,3,2] row_mask:0xf bank_mask:0xf
	s_waitcnt lgkmcnt(4)
	s_nop 1
	v_add_f32_dpp v206, v206, v206 quad_perm:[1,0,3,2] row_mask:0xf bank_mask:0xf
	s_waitcnt lgkmcnt(3)
	s_nop 1
	v_add_f32_dpp v208, v208, v208 quad_perm:[1,0,3,2] row_mask:0xf bank_mask:0xf
	s_waitcnt lgkmcnt(2)
	s_nop 1
	v_add_f32_dpp v164, v214, v214 quad_perm:[1,0,3,2] row_mask:0xf bank_mask:0xf
	s_waitcnt lgkmcnt(1)
	s_nop 1
	v_add_f32_dpp v166, v216, v216 quad_perm:[1,0,3,2] row_mask:0xf bank_mask:0xf
	s_waitcnt lgkmcnt(0)
	s_nop 1
	v_add_f32_dpp v162, v162, v162 quad_perm:[1,0,3,2] row_mask:0xf bank_mask:0xf
	s_waitcnt lgkmcnt(6)
	s_nop 1
	v_add_f32_dpp v200, v200, v200 quad_perm:[2,3,0,1] row_mask:0xf bank_mask:0xf
	s_waitcnt lgkmcnt(5)
	s_nop 1
	v_add_f32_dpp v204, v204, v204 quad_perm:[2,3,0,1] row_mask:0xf bank_mask:0xf
	s_waitcnt lgkmcnt(4)
	s_nop 1
	v_add_f32_dpp v206, v206, v206 quad_perm:[2,3,0,1] row_mask:0xf bank_mask:0xf
	s_waitcnt lgkmcnt(3)
	s_nop 1
	v_add_f32_dpp v208, v208, v208 quad_perm:[2,3,0,1] row_mask:0xf bank_mask:0xf
	s_waitcnt lgkmcnt(2)
	s_nop 1
	v_add_f32_dpp v164, v164, v164 quad_perm:[2,3,0,1] row_mask:0xf bank_mask:0xf
	s_waitcnt lgkmcnt(1)
	s_nop 1
	v_add_f32_dpp v166, v166, v166 quad_perm:[2,3,0,1] row_mask:0xf bank_mask:0xf
	s_waitcnt lgkmcnt(0)
	s_nop 1
	v_add_f32_dpp v162, v162, v162 quad_perm:[2,3,0,1] row_mask:0xf bank_mask:0xf
	s_waitcnt lgkmcnt(6)
	s_nop 1
	v_add_f32_dpp v201, v200, v200 row_shl:4 row_mask:0xf bank_mask:0x5
	v_add_f32_dpp v201, v200, v200 row_shr:4 row_mask:0xf bank_mask:0xa
	v_mov_b32_e32 v200, v201
	s_waitcnt lgkmcnt(5)
	s_nop 1
	v_add_f32_dpp v205, v204, v204 row_shl:4 row_mask:0xf bank_mask:0x5
	v_add_f32_dpp v205, v204, v204 row_shr:4 row_mask:0xf bank_mask:0xa
	v_mov_b32_e32 v204, v205
	s_waitcnt lgkmcnt(4)
	s_nop 1
	v_add_f32_dpp v207, v206, v206 row_shl:4 row_mask:0xf bank_mask:0x5
	v_add_f32_dpp v207, v206, v206 row_shr:4 row_mask:0xf bank_mask:0xa
	v_mov_b32_e32 v206, v207
	s_waitcnt lgkmcnt(3)
	s_nop 1
	v_add_f32_dpp v209, v208, v208 row_shl:4 row_mask:0xf bank_mask:0x5
	v_add_f32_dpp v209, v208, v208 row_shr:4 row_mask:0xf bank_mask:0xa
	v_mov_b32_e32 v208, v209
	s_waitcnt lgkmcnt(2)
	s_nop 1
	v_add_f32_dpp v165, v164, v164 row_shl:4 row_mask:0xf bank_mask:0x5
	v_add_f32_dpp v165, v164, v164 row_shr:4 row_mask:0xf bank_mask:0xa
	v_mov_b32_e32 v164, v165
	s_waitcnt lgkmcnt(1)
	s_nop 1
	v_add_f32_dpp v167, v166, v166 row_shl:4 row_mask:0xf bank_mask:0x5
	v_add_f32_dpp v167, v166, v166 row_shr:4 row_mask:0xf bank_mask:0xa
	v_mov_b32_e32 v166, v167
	s_waitcnt lgkmcnt(0)
	s_nop 1
	v_add_f32_dpp v163, v162, v162 row_shl:4 row_mask:0xf bank_mask:0x5
	v_add_f32_dpp v163, v162, v162 row_shr:4 row_mask:0xf bank_mask:0xa
	v_mov_b32_e32 v162, v163
	s_waitcnt lgkmcnt(6)
	s_nop 1
	v_add_f32_dpp v200, v200, v200 row_ror:8 row_mask:0xf bank_mask:0xf
	s_waitcnt lgkmcnt(5)
	s_nop 1
	v_add_f32_dpp v204, v204, v204 row_ror:8 row_mask:0xf bank_mask:0xf
	s_waitcnt lgkmcnt(4)
	s_nop 1
	v_add_f32_dpp v206, v206, v206 row_ror:8 row_mask:0xf bank_mask:0xf
	s_waitcnt lgkmcnt(3)
	s_nop 1
	v_add_f32_dpp v208, v208, v208 row_ror:8 row_mask:0xf bank_mask:0xf
	s_waitcnt lgkmcnt(2)
	s_nop 1
	v_add_f32_dpp v164, v164, v164 row_ror:8 row_mask:0xf bank_mask:0xf
	s_waitcnt lgkmcnt(1)
	s_nop 1
	v_add_f32_dpp v166, v166, v166 row_ror:8 row_mask:0xf bank_mask:0xf
	s_waitcnt lgkmcnt(0)
	s_nop 1
	v_add_f32_dpp v168, v162, v162 row_ror:8 row_mask:0xf bank_mask:0xf
	s_waitcnt lgkmcnt(6)
	v_mov_b32_e32 v201, v200
	s_nop 1
	v_permlane16_swap_b32_e32 v200, v201
	v_add_f32_e32 v200, v200, v201
	s_waitcnt lgkmcnt(5)
	v_mov_b32_e32 v205, v204
	s_nop 1
	v_permlane16_swap_b32_e32 v204, v205
	v_add_f32_e32 v204, v204, v205
	s_waitcnt lgkmcnt(4)
	v_mov_b32_e32 v207, v206
	s_nop 1
	v_permlane16_swap_b32_e32 v206, v207
	v_add_f32_e32 v206, v206, v207
	s_waitcnt lgkmcnt(3)
	v_mov_b32_e32 v209, v208
	s_nop 1
	v_permlane16_swap_b32_e32 v208, v209
	v_add_f32_e32 v208, v208, v209
	s_waitcnt lgkmcnt(2)
	v_mov_b32_e32 v165, v164
	s_nop 1
	v_permlane16_swap_b32_e32 v164, v165
	v_add_f32_e32 v162, v164, v165
	s_waitcnt lgkmcnt(1)
	v_mov_b32_e32 v167, v166
	s_nop 1
	v_permlane16_swap_b32_e32 v166, v167
	v_add_f32_e32 v164, v166, v167
	s_waitcnt lgkmcnt(0)
	v_mov_b32_e32 v169, v168
	s_nop 1
	v_permlane16_swap_b32_e32 v168, v169
	v_add_f32_e32 v166, v168, v169
	ds_bpermute_b32 v201, v193, v200
	ds_bpermute_b32 v203, v193, v202
	ds_bpermute_b32 v205, v193, v204
	ds_bpermute_b32 v207, v193, v206
	ds_bpermute_b32 v209, v193, v208
	ds_bpermute_b32 v163, v193, v162
	ds_bpermute_b32 v165, v193, v164
	ds_bpermute_b32 v167, v193, v166
	v_mov_b32_e32 v169, v211
	v_mov_b32_e32 v168, v210
	global_store_dwordx2 v[170:171], v[168:169], off offset:1536
	s_and_saveexec_b64 s[0:1], s[2:3]
	s_cbranch_execz .LBB0_42
	s_waitcnt lgkmcnt(7)
	v_add_f32_e32 v169, v200, v201
	s_waitcnt lgkmcnt(6)
	v_add_f32_e32 v168, v202, v203
	v_cndmask_b32_e64 v169, 0, v169, s[18:19]
	s_waitcnt lgkmcnt(0)
	v_add_f32_e32 v166, v166, v167
	v_add_f32_e32 v167, v204, v205
	v_cndmask_b32_e64 v168, v169, v168, s[16:17]
	v_add_f32_e32 v164, v164, v165
	v_add_f32_e32 v165, v206, v207
	v_cndmask_b32_e64 v167, v168, v167, s[14:15]
	v_add_f32_e32 v162, v162, v163
	v_add_f32_e32 v163, v208, v209
	v_cndmask_b32_e64 v165, v167, v165, s[12:13]
	v_cndmask_b32_e64 v163, v165, v163, s[10:11]
	v_cndmask_b32_e64 v162, v163, v162, s[8:9]
	v_cndmask_b32_e64 v162, v162, v164, s[6:7]
	v_cndmask_b32_e64 v162, v162, v166, s[4:5]
	v_add_f32_e32 v162, v181, v162
	v_mul_f32_e64 v163, |v162|, s46
	v_exp_f32_e32 v164, v163
	v_min_f32_e32 v165, 0, v162
	s_cmp_lg_u64 s[22:23], 0
	v_add_f32_e32 v166, 1.0, v164
	v_add_f32_e32 v162, -1.0, v166
	v_sub_f32_e32 v163, v162, v166
	v_add_f32_e32 v163, 1.0, v163
	v_sub_f32_e32 v162, v164, v162
	v_add_f32_e32 v167, v162, v163
	v_frexp_mant_f32_e32 v168, v166
	v_cvt_f64_f32_e32 v[162:163], v166
	v_frexp_exp_i32_f64_e32 v162, v[162:163]
	v_cmp_gt_f32_e32 vcc, s47, v168
	s_nop 1
	v_subbrev_co_u32_e32 v162, vcc, 0, v162, vcc
	v_sub_u32_e32 v163, 0, v162
	v_ldexp_f32 v166, v166, v163
	v_ldexp_f32 v163, v167, v163
	v_add_f32_e32 v167, -1.0, v166
	v_add_f32_e32 v170, 1.0, v166
	v_add_f32_e32 v168, 1.0, v167
	v_add_f32_e32 v171, -1.0, v170
	v_sub_f32_e32 v168, v166, v168
	v_sub_f32_e32 v166, v166, v171
	v_add_f32_e32 v168, v163, v168
	v_add_f32_e32 v163, v163, v166
	v_add_f32_e32 v166, v170, v163
	v_rcp_f32_e32 v171, v166
	v_add_f32_e32 v169, v167, v168
	v_sub_f32_e32 v167, v169, v167
	v_sub_f32_e32 v167, v168, v167
	v_sub_f32_e32 v168, v166, v170
	v_sub_f32_e32 v163, v163, v168
	v_mul_f32_e32 v168, v169, v171
	v_mul_f32_e32 v170, v166, v168
	v_fma_f32 v172, v168, v166, -v170
	v_fmac_f32_e32 v172, v168, v163
	v_add_f32_e32 v173, v170, v172
	v_sub_f32_e32 v174, v169, v173
	v_sub_f32_e32 v169, v169, v174
	v_sub_f32_e32 v170, v173, v170
	v_sub_f32_e32 v169, v169, v173
	v_add_f32_e32 v167, v167, v169
	v_sub_f32_e32 v169, v170, v172
	v_add_f32_e32 v167, v169, v167
	v_add_f32_e32 v169, v174, v167
	v_mul_f32_e32 v170, v171, v169
	v_mul_f32_e32 v172, v166, v170
	v_fma_f32 v166, v170, v166, -v172
	v_fmac_f32_e32 v166, v170, v163
	v_sub_f32_e32 v163, v174, v169
	v_add_f32_e32 v163, v167, v163
	v_add_f32_e32 v167, v172, v166
	v_sub_f32_e32 v173, v169, v167
	v_sub_f32_e32 v169, v169, v173
	v_sub_f32_e32 v172, v167, v172
	v_sub_f32_e32 v167, v169, v167
	v_add_f32_e32 v163, v163, v167
	v_sub_f32_e32 v166, v172, v166
	v_cvt_f32_i32_e32 v162, v162
	v_add_f32_e32 v163, v166, v163
	v_add_f32_e32 v166, v168, v170
	v_add_f32_e32 v163, v173, v163
	v_sub_f32_e32 v167, v166, v168
	v_mul_f32_e32 v163, v171, v163
	v_sub_f32_e32 v167, v170, v167
	v_add_f32_e32 v163, v167, v163
	v_mul_f32_e32 v170, 0x3f317218, v162
	v_add_f32_e32 v167, v166, v163
	v_fma_f32 v171, v162, s48, -v170
	v_mul_f32_e32 v168, v167, v167
	v_fmac_f32_e32 v171, 0xb102e308, v162
	v_sub_f32_e32 v162, v167, v166
	v_fmamk_f32 v169, v168, 0x3e9b6dac, v195
	v_sub_f32_e32 v162, v163, v162
	v_add_f32_e32 v163, v170, v171
	v_fmaak_f32 v169, v168, v169, 0x3f2aaada
	v_sub_f32_e32 v166, v163, v170
	v_ldexp_f32 v170, v167, 1
	v_mul_f32_e32 v167, v167, v168
	v_mul_f32_e32 v167, v167, v169
	v_add_f32_e32 v168, v170, v167
	v_sub_f32_e32 v169, v168, v170
	v_ldexp_f32 v162, v162, 1
	v_sub_f32_e32 v167, v167, v169
	v_add_f32_e32 v162, v162, v167
	v_add_f32_e32 v167, v168, v162
	v_sub_f32_e32 v168, v167, v168
	v_sub_f32_e32 v162, v162, v168
	v_add_f32_e32 v168, v163, v167
	v_sub_f32_e32 v169, v168, v163
	v_sub_f32_e32 v170, v168, v169
	v_sub_f32_e32 v166, v171, v166
	v_sub_f32_e32 v163, v163, v170
	v_sub_f32_e32 v167, v167, v169
	v_add_f32_e32 v163, v167, v163
	v_add_f32_e32 v167, v166, v162
	v_sub_f32_e32 v169, v167, v166
	v_sub_f32_e32 v170, v167, v169
	v_sub_f32_e32 v166, v166, v170
	v_sub_f32_e32 v162, v162, v169
	v_add_f32_e32 v163, v167, v163
	v_add_f32_e32 v162, v162, v166
	v_add_f32_e32 v166, v168, v163
	v_sub_f32_e32 v167, v166, v168
	v_sub_f32_e32 v163, v163, v167
	v_add_f32_e32 v162, v162, v163
	v_add_f32_e32 v162, v166, v162
	v_cmp_neq_f32_e32 vcc, s49, v164
	s_nop 1
	v_cndmask_b32_e32 v162, v197, v162, vcc
	v_cmp_ngt_f32_e32 vcc, -1.0, v164
	s_nop 1
	v_cndmask_b32_e32 v162, v198, v162, vcc
	v_cmp_neq_f32_e32 vcc, -1.0, v164
	s_nop 1
	v_cndmask_b32_e32 v162, v199, v162, vcc
	v_cmp_lt_f32_e64 vcc, |v164|, s50
	s_nop 1
	v_cndmask_b32_e32 v162, v162, v164, vcc
	v_sub_f32_e32 v162, v165, v162
	s_cselect_b64 vcc, -1, 0
	v_cndmask_b32_e32 v162, 0, v162, vcc
	v_lshl_add_u64 v[164:165], s[72:73], 0, v[182:183]
	s_cmp_eq_u64 s[30:31], 0
	global_store_dword v[164:165], v162, off
	s_cbranch_scc1 .LBB0_42
	global_store_dword v178, v162, s[30:31]
	s_branch .LBB0_42

.Lpost_getpc1:
	s_add_u32 s98, s98, (.LBB0_930-.Lpost_getpc1)&4294967295
	s_addc_u32 s99, s99, (.LBB0_930-.Lpost_getpc1)>>32
	s_setpc_b64 s[98:99]
	s_nop 0
	s_nop 0
.LBB0_124:
	v_mov_b32_e32 v14, v0
	s_cmp_gt_i32 s95, -1
	v_readfirstlane_b32 s2, v14
	s_cbranch_scc0 .LBB0_126
	s_lshl_b32 s4, s95, 7
	s_cbranch_execz .LBB0_127
	s_branch .LBB0_128
